# ret_contrib: log_sigmoid(decay) computed once per phase lane-parallel into a v244 lane table, units pick lgf/lgb with v_readlane instead of 2x ~125-op uniform math per unit
# baseline (speedup 1.0000x reference)
; __device__ __forceinline__ float log_sigmoid(float x) { return fminf(x, 0.f) - log1pf(expf(-fabsf(x))); }
; __device__ __forceinline__ void ret_contrib_unit(int unit, int next_unit, RetKV& pre, const bf16* RK, const bf16* RV, const float* decay_l, float* RETC, lds_t* lds, int tid, int lane, int wave) {
;     const int c = unit % 34, bh = unit / 34, h = bh & 3, b = bh >> 2;
;     lds_t* Kft = lds; lds_t* Kbt = lds + 64 * RT_LDK; lds_t* Vt = lds + 128 * RT_LDK;
;     const float lgf = log_sigmoid(decay_l[h]), lgb = log_sigmoid(decay_l[4 + h]);
;     { const int j = tid >> 2, d0 = (tid & 3) * 16; const float wf = __expf(lgf * (float)(127 - j)), wb = __expf(lgb * (float)j);
; #pragma unroll
.LBB0_540:
	s_lshl_b32 s84, s26, 3
	v_readlane_b32 s16, v252, 8
	v_readlane_b32 s26, v252, 18
	v_readlane_b32 s27, v252, 19
	v_readlane_b32 s30, v252, 22
	v_readlane_b32 s31, v252, 23
	s_lshl_b64 s[10:11], s[84:85], 2
	s_mov_b64 s[26:27], s[30:31]
	s_add_u32 s82, s26, s10
	s_movk_i32 s34, 0xff
	s_addc_u32 s83, s27, s11
	s_andn2_b64 vcc, exec, s[8:9]
	v_readlane_b32 s17, v252, 9
	v_readlane_b32 s18, v252, 10
	v_readlane_b32 s19, v252, 11
	v_readlane_b32 s20, v252, 12
	v_readlane_b32 s21, v252, 13
	v_readlane_b32 s22, v252, 14
	v_readlane_b32 s23, v252, 15
	v_readlane_b32 s24, v252, 16
	v_readlane_b32 s25, v252, 17
	v_readlane_b32 s28, v252, 20
	v_readlane_b32 s29, v252, 21
	s_cbranch_vccnz .LBB0_549
	s_ashr_i32 s7, s1, 6
	s_ashr_i32 s8, s1, 8
	s_cmp_lt_u32 s7, 4
	v_readlane_b32 s1, v255, 48
	s_cselect_b32 s1, 0, s1
	s_lshl_b32 s9, s7, 4
	s_and_b32 s10, s9, 32
	s_mul_i32 s9, s10, 0x110
	v_ashrrev_i32_e32 v19, 2, v0
	v_lshlrev_b32_e32 v2, 4, v0
	s_add_i32 s1, s1, s9
	s_lshl_b32 s9, s7, 5
	v_and_b32_e32 v18, 48, v2
	v_sub_u32_e32 v2, 0x7f, v19
	s_and_b32 s12, s9, 32
	v_cvt_f32_i32_e32 v30, v2
	s_mul_i32 s9, s12, 0x110
	v_and_b32_e32 v2, 31, v0
	v_mov_b32_e32 v3, s1
	s_movk_i32 s1, 0x110
	s_add_i32 s9, s9, 0
	v_mad_u32_u24 v6, v2, s1, v3
	v_lshrrev_b32_e32 v3, 1, v0
	v_and_b32_e32 v7, 16, v3
	v_mov_b32_e32 v3, s9
	v_mad_u32_u24 v8, v2, s1, v3
	s_ashr_i32 s9, s8, 31
	v_lshrrev_b32_e32 v3, 3, v0
	s_lshl_b32 s1, s7, 12
	v_lshlrev_b32_e32 v0, 5, v0
	s_ashr_i32 s7, s6, 31
	s_lshl_b64 s[8:9], s[8:9], 14
	v_and_or_b32 v3, v3, 7, s10
	s_and_b32 s1, s1, 0x2000
	v_and_b32_e32 v0, 0x400, v0
	s_lshl_b64 s[10:11], s[6:7], 15
	v_or_b32_e32 v0, s1, v0
	s_add_u32 s1, s10, s8
	v_cvt_f32_i32_e32 v31, v19
	s_addc_u32 s7, s11, s9
	v_or_b32_e32 v2, s12, v2
	s_add_u32 s8, s94, s1
	v_lshl_add_u32 v4, v19, 1, 0
	v_mul_u32_u24_e32 v5, 0x110, v18
	v_lshlrev_b32_e32 v9, 8, v3
	v_lshlrev_b32_e32 v2, 2, v2
	v_mov_b32_e32 v3, v1
	s_addc_u32 s9, s95, s7
	s_ashr_i32 s1, s0, 31
	v_lshl_add_u64 v[20:21], s[8:9], 0, v[2:3]
	s_lshl_b64 s[8:9], s[0:1], 15
	v_or_b32_e32 v22, 0x6801b00, v9
	v_mov_b32_e32 v23, v1
	v_or_b32_e32 v24, 0x6801300, v9
	v_mov_b32_e32 v25, v1
	v_or_b32_e32 v26, 0x6800b00, v9
	v_mov_b32_e32 v27, v1
	v_or_b32_e32 v28, 0x6800300, v9
	v_mov_b32_e32 v29, v1
	v_add_u32_e32 v32, v4, v5
	v_add_u32_e32 v33, v6, v7
	v_add_u32_e32 v34, v8, v7
	v_mbcnt_lo_u32_b32 v3, -1, 0
	v_mbcnt_hi_u32_b32 v3, -1, v3
	v_and_b32_e32 v3, 7, v3
	v_lshlrev_b32_e32 v3, 2, v3
	global_load_dword v3, v3, s[82:83]
	s_waitcnt vmcnt(0) lgkmcnt(0)
	v_max_f32_e32 v4, v3, v3
	v_min_f32_e32 v6, 0, v4
	v_mul_f32_e64 v4, |v3|, s35
	v_fma_f32 v5, |v3|, s35, -v4
	v_rndne_f32_e32 v7, v4
	v_fma_f32 v5, |v3|, s37, v5
	v_sub_f32_e32 v4, v4, v7
	v_add_f32_e32 v4, v4, v5
	v_exp_f32_e32 v4, v4
	v_cvt_i32_f32_e32 v5, v7
	v_cmp_ngt_f32_e64 vcc, |v3|, s38
	v_ldexp_f32 v4, v4, v5
	s_nop 0
	v_cndmask_b32_e32 v4, 0, v4, vcc
	v_cmp_nlt_f32_e64 vcc, |v3|, s39
	s_nop 1
	v_cndmask_b32_e32 v3, v219, v4, vcc
	v_add_f32_e32 v7, 1.0, v3
	v_add_f32_e32 v4, -1.0, v7
	v_sub_f32_e32 v5, v4, v7
	v_add_f32_e32 v5, 1.0, v5
	v_sub_f32_e32 v4, v3, v4
	v_add_f32_e32 v8, v4, v5
	v_frexp_mant_f32_e32 v4, v7
	v_cmp_gt_f32_e32 vcc, s48, v4
	v_cvt_f64_f32_e32 v[4:5], v7
	v_frexp_exp_i32_f64_e32 v4, v[4:5]
	v_subbrev_co_u32_e32 v4, vcc, 0, v4, vcc
	v_sub_u32_e32 v5, 0, v4
	v_ldexp_f32 v7, v7, v5
	v_ldexp_f32 v5, v8, v5
	v_add_f32_e32 v8, -1.0, v7
	v_add_f32_e32 v9, 1.0, v8
	v_sub_f32_e32 v9, v7, v9
	v_add_f32_e32 v9, v5, v9
	v_add_f32_e32 v10, v8, v9
	v_sub_f32_e32 v8, v8, v10
	v_add_f32_e32 v8, v9, v8
	v_add_f32_e32 v9, 1.0, v7
	v_add_f32_e32 v11, -1.0, v9
	v_sub_f32_e32 v7, v7, v11
	v_add_f32_e32 v5, v5, v7
	v_add_f32_e32 v7, v9, v5
	v_sub_f32_e32 v9, v9, v7
	v_add_f32_e32 v5, v5, v9
	v_rcp_f32_e32 v9, v7
	v_cvt_f32_i32_e32 v4, v4
	v_cmp_neq_f32_e32 vcc, s46, v3
	v_mul_f32_e32 v11, v10, v9
	v_mul_f32_e32 v12, v7, v11
	v_fma_f32 v13, v11, v7, -v12
	v_fmac_f32_e32 v13, v11, v5
	v_add_f32_e32 v14, v12, v13
	v_sub_f32_e32 v15, v10, v14
	v_sub_f32_e32 v10, v10, v15
	v_sub_f32_e32 v12, v14, v12
	v_sub_f32_e32 v10, v10, v14
	v_add_f32_e32 v8, v8, v10
	v_sub_f32_e32 v10, v12, v13
	v_add_f32_e32 v8, v10, v8
	v_add_f32_e32 v10, v15, v8
	v_mul_f32_e32 v12, v9, v10
	v_mul_f32_e32 v13, v7, v12
	v_fma_f32 v7, v12, v7, -v13
	v_fmac_f32_e32 v7, v12, v5
	v_sub_f32_e32 v5, v15, v10
	v_add_f32_e32 v5, v8, v5
	v_add_f32_e32 v8, v13, v7
	v_sub_f32_e32 v14, v10, v8
	v_sub_f32_e32 v10, v10, v14
	v_sub_f32_e32 v13, v8, v13
	v_sub_f32_e32 v8, v10, v8
	v_add_f32_e32 v5, v5, v8
	v_sub_f32_e32 v7, v13, v7
	v_add_f32_e32 v5, v7, v5
	v_add_f32_e32 v7, v11, v12
	v_add_f32_e32 v5, v14, v5
	v_sub_f32_e32 v8, v7, v11
	v_mul_f32_e32 v5, v9, v5
	v_sub_f32_e32 v8, v12, v8
	v_add_f32_e32 v5, v8, v5
	v_mul_f32_e32 v11, 0x3f317218, v4
	v_add_f32_e32 v8, v7, v5
	v_fma_f32 v12, v4, s49, -v11
	v_mul_f32_e32 v9, v8, v8
	v_fmac_f32_e32 v12, 0xb102e308, v4
	v_sub_f32_e32 v4, v8, v7
	v_fmamk_f32 v10, v9, 0x3e9b6dac, v217
	v_sub_f32_e32 v4, v5, v4
	v_add_f32_e32 v5, v11, v12
	v_fmaak_f32 v10, v9, v10, 0x3f2aaada
	v_sub_f32_e32 v7, v5, v11
	v_ldexp_f32 v11, v8, 1
	v_mul_f32_e32 v8, v8, v9
	v_mul_f32_e32 v8, v8, v10
	v_add_f32_e32 v9, v11, v8
	v_sub_f32_e32 v10, v9, v11
	v_ldexp_f32 v4, v4, 1
	v_sub_f32_e32 v8, v8, v10
	v_add_f32_e32 v4, v4, v8
	v_add_f32_e32 v8, v9, v4
	v_sub_f32_e32 v9, v8, v9
	v_sub_f32_e32 v4, v4, v9
	v_add_f32_e32 v9, v5, v8
	v_sub_f32_e32 v10, v9, v5
	v_sub_f32_e32 v11, v9, v10
	v_sub_f32_e32 v7, v12, v7
	v_sub_f32_e32 v5, v5, v11
	v_sub_f32_e32 v8, v8, v10
	v_add_f32_e32 v5, v8, v5
	v_add_f32_e32 v8, v7, v4
	v_sub_f32_e32 v10, v8, v7
	v_sub_f32_e32 v11, v8, v10
	v_sub_f32_e32 v7, v7, v11
	v_sub_f32_e32 v4, v4, v10
	v_add_f32_e32 v5, v8, v5
	v_add_f32_e32 v4, v4, v7
	v_add_f32_e32 v7, v9, v5
	v_sub_f32_e32 v8, v7, v9
	v_sub_f32_e32 v5, v5, v8
	v_add_f32_e32 v4, v4, v5
	v_add_f32_e32 v4, v7, v4
	v_cndmask_b32_e32 v4, v219, v4, vcc
	v_cmp_lt_f32_e64 vcc, |v3|, s50
	s_nop 1
	v_cndmask_b32_e32 v3, v4, v3, vcc
	v_sub_f32_e32 v4, v6, v3
	v_mov_b32_e32 v244, v4
	s_branch .LBB0_544

; #define LAS __attribute__((address_space(3)))
; __device__ __forceinline__ unsigned f2bf(float f) { unsigned u = __builtin_bit_cast(unsigned, f); return (u + 0x7fffu + ((u >> 16) & 1u)) >> 16; }
; __device__ __forceinline__ float log_sigmoid(float x) { return fminf(x, 0.f) - log1pf(expf(-fabsf(x))); }
; __device__ __forceinline__ void ret_contrib_unit(int unit, int next_unit, RetKV& pre, const bf16* RK, const bf16* RV, const float* decay_l, float* RETC, lds_t* lds, int tid, int lane, int wave) {
;     ...
;     const float lgf = log_sigmoid(decay_l[h]), lgb = log_sigmoid(decay_l[4 + h]);
;     { const int j = tid >> 2, d0 = (tid & 3) * 16; const float wf = __expf(lgf * (float)(127 - j)), wb = __expf(lgb * (float)j);
; #pragma unroll
;         for (int q = 0; q < 2; ++q) { const v4u kw = pre.k[q], vw = pre.v[q];
; #pragma unroll
;             for (int e = 0; e < 4; ++e) { const unsigned kk = kw[e], vv = vw[e]; const int d = d0 + q * 8 + 2 * e; const float k0 = bflo(kk), k1 = bfhi(kk);
;                 *(LAS unsigned short*)(Kft + d * RT_LDK + j * 2) = (unsigned short)f2bf(k0 * wf); *(LAS unsigned short*)(Kft + (d + 1) * RT_LDK + j * 2) = (unsigned short)f2bf(k1 * wf);
;                 *(LAS unsigned short*)(Kbt + d * RT_LDK + j * 2) = (unsigned short)f2bf(k0 * wb); *(LAS unsigned short*)(Kbt + (d + 1) * RT_LDK + j * 2) = (unsigned short)f2bf(k1 * wb);
;                 *(LAS unsigned short*)(Vt + d * RT_LDK + j * 2) = (unsigned short)(vv & 0xffffu); *(LAS unsigned short*)(Vt + (d + 1) * RT_LDK + j * 2) = (unsigned short)(vv >> 16); } } }
;     __syncthreads();
;     if (next_unit >= 0) ret_contrib_load(pre, next_unit, RK, RV, tid);
.LBB0_544:
	s_mov_b32 s7, s6
	s_add_i32 s6, s6, s0
	s_cmp_ge_i32 s6, s14
	s_cselect_b64 s[10:11], -1, 0
	s_cmp_lt_i32 s6, s14
	s_mul_hi_i32 s7, s7, 0x78787879
	s_cselect_b32 s1, s6, -1
	s_lshr_b32 s12, s7, 31
	s_lshr_b32 s7, s7, 4
	s_add_i32 s7, s7, s12
	s_and_b32 s7, s7, 3
	s_lshl_b32 s7, s7, 2
	s_lshr_b32 s18, s7, 2
	v_readlane_b32 s19, v244, s18
	s_add_u32 s18, s18, 4
	v_readlane_b32 s20, v244, s18
	s_cmp_lt_i32 s1, 0
	v_mov_b32_e32 v4, s19
	v_mov_b32_e32 v2, s20
	v_mul_f32_e32 v3, v4, v30
	v_mul_f32_e32 v3, 0x3fb8aa3b, v3
	v_exp_f32_e32 v3, v3
	s_waitcnt vmcnt(16)
	v_lshlrev_b32_e32 v4, 16, v118
	v_mul_f32_e32 v2, v2, v31
	v_mul_f32_e32 v2, 0x3fb8aa3b, v2
	v_mul_f32_e32 v6, v3, v4
	v_exp_f32_e32 v2, v2
	v_bfe_u32 v7, v6, 16, 1
	v_and_b32_e32 v5, 0xffff0000, v118
	v_add3_u32 v6, v6, v7, s33
	ds_write_b16_d16_hi v32, v6
	v_mul_f32_e32 v6, v3, v5
	v_bfe_u32 v7, v6, 16, 1
	v_add3_u32 v6, v6, v7, s33
	v_mul_f32_e32 v4, v2, v4
	ds_write_b16_d16_hi v32, v6 offset:272
	v_bfe_u32 v6, v4, 16, 1
	v_add3_u32 v4, v4, v6, s33
	ds_write_b16_d16_hi v32, v4 offset:17408
	v_mul_f32_e32 v4, v2, v5
	v_bfe_u32 v5, v4, 16, 1
	v_add3_u32 v4, v4, v5, s33
	ds_write_b16_d16_hi v32, v4 offset:17680
	ds_write_b16 v32, v122 offset:34816
	ds_write_b16_d16_hi v32, v122 offset:35088
	v_lshlrev_b32_e32 v4, 16, v119
	v_mul_f32_e32 v6, v3, v4
	v_bfe_u32 v7, v6, 16, 1
	v_and_b32_e32 v5, 0xffff0000, v119
	v_add3_u32 v6, v6, v7, s33
	ds_write_b16_d16_hi v32, v6 offset:544
	v_mul_f32_e32 v6, v3, v5
	v_bfe_u32 v7, v6, 16, 1
	v_add3_u32 v6, v6, v7, s33
	v_mul_f32_e32 v4, v2, v4
	ds_write_b16_d16_hi v32, v6 offset:816
	v_bfe_u32 v6, v4, 16, 1
	v_add3_u32 v4, v4, v6, s33
	ds_write_b16_d16_hi v32, v4 offset:17952
	v_mul_f32_e32 v4, v2, v5
	v_bfe_u32 v5, v4, 16, 1
	v_add3_u32 v4, v4, v5, s33
	ds_write_b16_d16_hi v32, v4 offset:18224
	ds_write_b16 v32, v123 offset:35360
	ds_write_b16_d16_hi v32, v123 offset:35632
	v_lshlrev_b32_e32 v4, 16, v120
	v_mul_f32_e32 v6, v3, v4
	v_bfe_u32 v7, v6, 16, 1
	v_and_b32_e32 v5, 0xffff0000, v120
	v_add3_u32 v6, v6, v7, s33
	ds_write_b16_d16_hi v32, v6 offset:1088
	v_mul_f32_e32 v6, v3, v5
	v_bfe_u32 v7, v6, 16, 1
	v_add3_u32 v6, v6, v7, s33
	v_mul_f32_e32 v4, v2, v4
	ds_write_b16_d16_hi v32, v6 offset:1360
	v_bfe_u32 v6, v4, 16, 1
	v_add3_u32 v4, v4, v6, s33
	ds_write_b16_d16_hi v32, v4 offset:18496
	v_mul_f32_e32 v4, v2, v5
	v_bfe_u32 v5, v4, 16, 1
	v_add3_u32 v4, v4, v5, s33
	ds_write_b16_d16_hi v32, v4 offset:18768
	ds_write_b16 v32, v124 offset:35904
	ds_write_b16_d16_hi v32, v124 offset:36176
	v_lshlrev_b32_e32 v4, 16, v121
	v_mul_f32_e32 v6, v3, v4
	v_bfe_u32 v7, v6, 16, 1
	v_and_b32_e32 v5, 0xffff0000, v121
	v_add3_u32 v6, v6, v7, s33
	ds_write_b16_d16_hi v32, v6 offset:1632
	v_mul_f32_e32 v6, v3, v5
	v_bfe_u32 v7, v6, 16, 1
	v_add3_u32 v6, v6, v7, s33
	v_mul_f32_e32 v4, v2, v4
	ds_write_b16_d16_hi v32, v6 offset:1904
	v_bfe_u32 v6, v4, 16, 1
	v_add3_u32 v4, v4, v6, s33
	ds_write_b16_d16_hi v32, v4 offset:19040
	v_mul_f32_e32 v4, v2, v5
	v_bfe_u32 v5, v4, 16, 1
	v_add3_u32 v4, v4, v5, s33
	ds_write_b16_d16_hi v32, v4 offset:19312
	ds_write_b16 v32, v125 offset:36448
	ds_write_b16_d16_hi v32, v125 offset:36720
	v_lshlrev_b32_e32 v4, 16, v114
	v_mul_f32_e32 v6, v3, v4
	v_bfe_u32 v7, v6, 16, 1
	v_and_b32_e32 v5, 0xffff0000, v114
	v_add3_u32 v6, v6, v7, s33
	ds_write_b16_d16_hi v32, v6 offset:2176
	v_mul_f32_e32 v6, v3, v5
	v_bfe_u32 v7, v6, 16, 1
	v_add3_u32 v6, v6, v7, s33
	v_mul_f32_e32 v4, v2, v4
	ds_write_b16_d16_hi v32, v6 offset:2448
	v_bfe_u32 v6, v4, 16, 1
	v_add3_u32 v4, v4, v6, s33
	ds_write_b16_d16_hi v32, v4 offset:19584
	v_mul_f32_e32 v4, v2, v5
	v_bfe_u32 v5, v4, 16, 1
	v_add3_u32 v4, v4, v5, s33
	ds_write_b16_d16_hi v32, v4 offset:19856
	ds_write_b16 v32, v126 offset:36992
	ds_write_b16_d16_hi v32, v126 offset:37264
	v_lshlrev_b32_e32 v4, 16, v115
	v_mul_f32_e32 v6, v3, v4
	v_bfe_u32 v7, v6, 16, 1
	v_and_b32_e32 v5, 0xffff0000, v115
	v_add3_u32 v6, v6, v7, s33
	ds_write_b16_d16_hi v32, v6 offset:2720
	v_mul_f32_e32 v6, v3, v5
	v_bfe_u32 v7, v6, 16, 1
	v_add3_u32 v6, v6, v7, s33
	v_mul_f32_e32 v4, v2, v4
	ds_write_b16_d16_hi v32, v6 offset:2992
	v_bfe_u32 v6, v4, 16, 1
	v_add3_u32 v4, v4, v6, s33
	ds_write_b16_d16_hi v32, v4 offset:20128
	v_mul_f32_e32 v4, v2, v5
	v_bfe_u32 v5, v4, 16, 1
	v_add3_u32 v4, v4, v5, s33
	ds_write_b16_d16_hi v32, v4 offset:20400
	ds_write_b16 v32, v127 offset:37536
	ds_write_b16_d16_hi v32, v127 offset:37808
	v_lshlrev_b32_e32 v4, 16, v116
	v_mul_f32_e32 v6, v3, v4
	v_bfe_u32 v7, v6, 16, 1
	v_and_b32_e32 v5, 0xffff0000, v116
	v_add3_u32 v6, v6, v7, s33
	ds_write_b16_d16_hi v32, v6 offset:3264
	v_mul_f32_e32 v6, v3, v5
	v_bfe_u32 v7, v6, 16, 1
	v_add3_u32 v6, v6, v7, s33
	v_mul_f32_e32 v4, v2, v4
	ds_write_b16_d16_hi v32, v6 offset:3536
	v_bfe_u32 v6, v4, 16, 1
	v_add3_u32 v4, v4, v6, s33
	ds_write_b16_d16_hi v32, v4 offset:20672
	v_mul_f32_e32 v4, v2, v5
	v_bfe_u32 v5, v4, 16, 1
	v_add3_u32 v4, v4, v5, s33
	ds_write_b16_d16_hi v32, v4 offset:20944
	ds_write_b16 v32, v128 offset:38080
	ds_write_b16_d16_hi v32, v128 offset:38352
	v_lshlrev_b32_e32 v4, 16, v117
	v_mul_f32_e32 v6, v3, v4
	v_and_b32_e32 v5, 0xffff0000, v117
	v_bfe_u32 v7, v6, 16, 1
	v_add3_u32 v6, v6, v7, s33
	v_mul_f32_e32 v3, v3, v5
	ds_write_b16_d16_hi v32, v6 offset:3808
	v_bfe_u32 v6, v3, 16, 1
	v_add3_u32 v3, v3, v6, s33
	ds_write_b16_d16_hi v32, v3 offset:4080
	v_mul_f32_e32 v3, v2, v4
	v_bfe_u32 v4, v3, 16, 1
	v_add3_u32 v3, v3, v4, s33
	v_mul_f32_e32 v2, v2, v5
	ds_write_b16_d16_hi v32, v3 offset:21216
	v_bfe_u32 v3, v2, 16, 1
	v_add3_u32 v2, v2, v3, s33
	ds_write_b16_d16_hi v32, v2 offset:21488
	ds_write_b16 v32, v129 offset:38624
	ds_write_b16_d16_hi v32, v129 offset:38896
	s_waitcnt lgkmcnt(0)
	s_barrier
	s_cbranch_scc1 .LBB0_543
	s_mul_hi_u32 s12, s1, 0xf0f0f0f1
	s_lshr_b32 s7, s12, 5
	s_mul_i32 s13, s7, 34
	s_sub_i32 s13, s1, s13
	s_lshr_b32 s1, s12, 7
	s_lshl_b32 s15, s13, 7
	s_cmp_gt_u32 s13, 31
	s_mov_b64 s[12:13], -1
	s_cbranch_scc0 .LBB0_547
	s_lshl_b32 s12, s1, 8
	s_add_i32 s12, s15, s12
	s_add_i32 s16, s12, 0x7000
	s_mov_b64 s[12:13], 0
